# LN row-stat exchange: plain slot stores + per-wave flag words polled with one sc1 load instead of an atomic counter
# baseline (speedup 1.0000x reference)
;     __device__ __forceinline__ bool run(const Acc& v, int pm, int pn, int wr, int wc, int fr, int fq, LAS unsigned char* lds, int wid, int lane) const {
;     ...
;         const int row = wid * 32 + (lane & 31);
;         if (lane < 32) {
;             const f32x2 a = P[row * 4 + 0], b = P[row * 4 + 1], c = P[row * 4 + 2], d = P[row * 4 + 3];
;             const float mt = (a.x + b.x + c.x + d.x) * 0.25f;
;             const float da = a.x - mt, db = b.x - mt, dc = c.x - mt, dd = d.x - mt;
;             const float m2 = (a.y + b.y) + (c.y + d.y) + 64.0f * ((da * da + db * db) + (dc * dc + dd * dd));
;             unsigned long long* slot = (unsigned long long*)xbuf + ((size_t)(pm * BM + row) * 4 + pn);
;             __hip_atomic_store(slot, ((unsigned long long)__float_as_uint(m2) << 32) | __float_as_uint(mt), __ATOMIC_RELAXED, __HIP_MEMORY_SCOPE_AGENT);
;         }
;         asm volatile("s_waitcnt vmcnt(0)" ::: "memory");
;         if (lane == 0) __hip_atomic_fetch_add(cnt + 64 * pm, 1u, __ATOMIC_RELAXED, __HIP_MEMORY_SCOPE_AGENT);
;         if (wid == 0) {
;             bool dead = false; const unsigned long long t0 = __builtin_amdgcn_s_memrealtime(); const unsigned want = 32u;
;             for (;;) {
;                 if ((unsigned)__builtin_amdgcn_readfirstlane(__hip_atomic_load(cnt + 64 * pm, __ATOMIC_RELAXED, __HIP_MEMORY_SCOPE_AGENT)) >= want) break;
;                 if (__builtin_amdgcn_s_memrealtime() - t0 > 2000000ull) {
;                     if (lane == 0) { unsigned expect = 0u; __hip_atomic_compare_exchange_strong(tmo + 1, &expect, code | (unsigned)(pm & 0xff), __ATOMIC_RELAXED, __ATOMIC_RELAXED, __HIP_MEMORY_SCOPE_AGENT);
;                                      __hip_atomic_store(tmo, 1u, __ATOMIC_RELAXED, __HIP_MEMORY_SCOPE_AGENT); }
;                     dead = true; break; }
.LBB0_788:
	s_or_b64 exec, exec, s[0:1]
	v_and_b32_e32 v162, 31, v179
	v_readlane_b32 s0, v255, 4
	s_waitcnt lgkmcnt(0)
	s_barrier
	s_add_u32 s6, s28, 0x1e00000
	v_lshl_or_b32 v165, s0, 5, v162
	v_add_u32_e32 v162, s4, v165
	s_addc_u32 s7, s29, 0
	v_cmp_gt_u32_e64 s[40:41], 32, v164
	v_ashrrev_i32_e32 v163, 31, v162
	s_and_saveexec_b64 s[0:1], s[40:41]
	s_cbranch_execz .LBB0_790
	v_lshl_add_u32 v170, v165, 5, 0
	ds_read_b128 v[166:169], v170
	ds_read_b128 v[170:173], v170 offset:16
	s_ashr_i32 s3, s2, 31
	s_waitcnt lgkmcnt(1)
	v_add_f32_e32 v174, v166, v168
	s_waitcnt lgkmcnt(0)
	v_add_f32_e32 v174, v174, v170
	v_add_f32_e32 v175, v174, v172
	v_fmamk_f32 v166, v175, 0xbe800000, v166
	v_fmac_f32_e32 v168, 0xbe800000, v175
	v_fmamk_f32 v170, v175, 0xbe800000, v170
	v_fmac_f32_e32 v172, 0xbe800000, v175
	v_mul_f32_e32 v177, v166, v166
	v_mul_f32_e32 v181, v168, v168
	v_mul_f32_e32 v183, v170, v170
	v_mul_f32_e32 v185, v172, v172
	v_mov_b32_e32 v176, v167
	v_mov_b32_e32 v180, v169
	v_mov_b32_e32 v182, v171
	v_mov_b32_e32 v184, v173
	v_pk_add_f32 v[166:167], v[176:177], v[180:181]
	v_pk_add_f32 v[168:169], v[182:183], v[184:185]
	v_mul_f32_e32 v174, 0x3e800000, v175
	v_pk_add_f32 v[166:167], v[166:167], v[168:169]
	v_lshlrev_b64 v[168:169], 5, v[162:163]
	v_fmac_f32_e32 v166, 0x42800000, v167
	v_lshl_add_u64 v[168:169], s[6:7], 0, v[168:169]
	v_lshl_add_u64 v[168:169], s[2:3], 3, v[168:169]
	v_mov_b32_e32 v175, v166
	flat_store_dwordx2 v[168:169], v[174:175]
.LBB0_790:
	s_or_b64 exec, exec, s[0:1]
	s_waitcnt vmcnt(0)
	v_cmp_ne_u32_e64 s[44:45], 0, v164
	v_cmp_eq_u32_e64 s[42:43], 0, v164
	s_and_saveexec_b64 s[0:1], s[42:43]
	s_cbranch_execz .LBB0_793
	s_mov_b64 s[2:3], exec
	v_mbcnt_lo_u32_b32 v164, s2, 0
	v_mbcnt_hi_u32_b32 v164, s3, v164
	v_cmp_eq_u32_e32 vcc, 0, v164
	s_and_b64 s[8:9], exec, vcc
	s_mov_b64 exec, s[8:9]
	s_cbranch_execz .LBB0_793
	s_lshl_b32 s8, s68, 6
	s_ashr_i32 s9, s8, 31
	s_lshl_b64 s[8:9], s[8:9], 2
	v_readlane_b32 s5, v254, 2
	s_add_u32 s8, s5, s8
	v_readlane_b32 s5, v254, 3
	s_addc_u32 s9, s5, s9
	v_readlane_b32 s5, v254, 49
	v_readlane_b32 s2, v253, 2
	s_lshr_b32 s5, s5, 6
	s_lshl_b32 s5, s5, 3
	s_add_u32 s5, s5, s2
	s_lshl_b32 s5, s5, 2
	s_add_u32 s8, s8, s5
	s_addc_u32 s9, s9, 0
	v_mov_b32_e32 v164, 1
	global_store_dword v193, v164, s[8:9]
.LBB0_793:
	s_or_b64 exec, exec, s[0:1]
	v_readlane_b32 s0, v255, 7
	s_cmp_gt_u32 s0, 63
	s_cbranch_scc1 .LBB0_810
	v_mbcnt_lo_u32_b32 v186, -1, 0
	v_mbcnt_hi_u32_b32 v186, -1, v186
	v_and_b32_e32 v186, 31, v186
	v_lshlrev_b32_e32 v186, 2, v186
	s_memrealtime s[0:1]
	s_lshl_b32 s2, s68, 6
	s_ashr_i32 s3, s2, 31
	s_lshl_b64 s[2:3], s[2:3], 2
	v_readlane_b32 s5, v254, 2
	s_add_u32 s2, s5, s2
	v_readlane_b32 s5, v254, 3
	s_addc_u32 s3, s5, s3
	s_branch .LBB0_797

;     __device__ __forceinline__ bool run(const Acc& v, int pm, int pn, int wr, int wc, int fr, int fq, LAS unsigned char* lds, int wid, int lane) const {
;     ...
;         if (wid == 0) {
;             bool dead = false; const unsigned long long t0 = __builtin_amdgcn_s_memrealtime(); const unsigned want = 32u;
;             for (;;) {
;                 if ((unsigned)__builtin_amdgcn_readfirstlane(__hip_atomic_load(cnt + 64 * pm, __ATOMIC_RELAXED, __HIP_MEMORY_SCOPE_AGENT)) >= want) break;
;                 if (__builtin_amdgcn_s_memrealtime() - t0 > 2000000ull) {
;                     if (lane == 0) { unsigned expect = 0u; __hip_atomic_compare_exchange_strong(tmo + 1, &expect, code | (unsigned)(pm & 0xff), __ATOMIC_RELAXED, __ATOMIC_RELAXED, __HIP_MEMORY_SCOPE_AGENT);
;                                      __hip_atomic_store(tmo, 1u, __ATOMIC_RELAXED, __HIP_MEMORY_SCOPE_AGENT); }
;                     dead = true; break; }
;                 __builtin_amdgcn_s_sleep(2);
;             }
.LBB0_797:
	global_load_dword v164, v186, s[2:3] sc1
	s_mov_b64 s[8:9], -1
	s_mov_b64 s[10:11], -1
	s_waitcnt vmcnt(0)
	v_cmp_eq_u32_e32 vcc, 0, v164
	s_nop 1
	s_cmp_eq_u64 vcc, 0
	s_cbranch_scc1 .LBB0_796
	s_memrealtime s[8:9]
	v_mov_b64_e32 v[166:167], 0x1e8481
	s_waitcnt lgkmcnt(0)
	s_sub_u32 s8, s8, s0
	s_subb_u32 s9, s9, s1
	v_cmp_lt_u64_e32 vcc, s[8:9], v[166:167]
	s_cbranch_vccz .LBB0_795
	s_mov_b64 s[10:11], 0
	s_sleep 2
	s_branch .LBB0_795

;     __device__ __forceinline__ bool run(const Acc& v, int pm, int pn, int wr, int wc, int fr, int fq, LAS unsigned char* lds, int wid, int lane) const {
;     ...
;         const int row = wid * 32 + (lane & 31);
;         if (lane < 32) {
;             const f32x2 a = P[row * 4 + 0], b = P[row * 4 + 1], c = P[row * 4 + 2], d = P[row * 4 + 3];
;             const float mt = (a.x + b.x + c.x + d.x) * 0.25f;
;             const float da = a.x - mt, db = b.x - mt, dc = c.x - mt, dd = d.x - mt;
;             const float m2 = (a.y + b.y) + (c.y + d.y) + 64.0f * ((da * da + db * db) + (dc * dc + dd * dd));
;             unsigned long long* slot = (unsigned long long*)xbuf + ((size_t)(pm * BM + row) * 4 + pn);
;             __hip_atomic_store(slot, ((unsigned long long)__float_as_uint(m2) << 32) | __float_as_uint(mt), __ATOMIC_RELAXED, __HIP_MEMORY_SCOPE_AGENT);
;         }
;         asm volatile("s_waitcnt vmcnt(0)" ::: "memory");
;         if (lane == 0) __hip_atomic_fetch_add(cnt + 64 * pm, 1u, __ATOMIC_RELAXED, __HIP_MEMORY_SCOPE_AGENT);
;         if (wid == 0) {
;             bool dead = false; const unsigned long long t0 = __builtin_amdgcn_s_memrealtime(); const unsigned want = 32u;
;             for (;;) {
;                 if ((unsigned)__builtin_amdgcn_readfirstlane(__hip_atomic_load(cnt + 64 * pm, __ATOMIC_RELAXED, __HIP_MEMORY_SCOPE_AGENT)) >= want) break;
;                 if (__builtin_amdgcn_s_memrealtime() - t0 > 2000000ull) {
;                     if (lane == 0) { unsigned expect = 0u; __hip_atomic_compare_exchange_strong(tmo + 1, &expect, code | (unsigned)(pm & 0xff), __ATOMIC_RELAXED, __ATOMIC_RELAXED, __HIP_MEMORY_SCOPE_AGENT);
;                                      __hip_atomic_store(tmo, 1u, __ATOMIC_RELAXED, __HIP_MEMORY_SCOPE_AGENT); }
;                     dead = true; break; }
;                 __builtin_amdgcn_s_sleep(2);
;             }
;             __builtin_amdgcn_fence(__ATOMIC_ACQUIRE, "agent");
;             if (lane == 0) flag[0] = dead ? 1u : 0u;
.LBB0_864:
	s_or_b64 exec, exec, s[0:1]
	v_and_b32_e32 v162, 31, v179
	v_readlane_b32 s0, v255, 4
	s_waitcnt lgkmcnt(0)
	s_barrier
	s_add_u32 s6, s6, 0x1e80000
	v_lshl_or_b32 v165, s0, 5, v162
	v_add_u32_e32 v162, s24, v165
	s_addc_u32 s7, s7, 0
	v_cmp_gt_u32_e64 s[40:41], 32, v164
	v_ashrrev_i32_e32 v163, 31, v162
	s_and_saveexec_b64 s[0:1], s[40:41]
	s_cbranch_execz .LBB0_866
	v_lshl_add_u32 v170, v165, 5, 0
	ds_read_b128 v[166:169], v170
	ds_read_b128 v[170:173], v170 offset:16
	s_ashr_i32 s3, s2, 31
	s_waitcnt lgkmcnt(1)
	v_add_f32_e32 v174, v166, v168
	s_waitcnt lgkmcnt(0)
	v_add_f32_e32 v174, v174, v170
	v_add_f32_e32 v175, v174, v172
	v_fmamk_f32 v166, v175, 0xbe800000, v166
	v_fmac_f32_e32 v168, 0xbe800000, v175
	v_fmamk_f32 v170, v175, 0xbe800000, v170
	v_fmac_f32_e32 v172, 0xbe800000, v175
	v_mul_f32_e32 v177, v166, v166
	v_mul_f32_e32 v181, v168, v168
	v_mul_f32_e32 v183, v170, v170
	v_mul_f32_e32 v185, v172, v172
	v_mov_b32_e32 v176, v167
	v_mov_b32_e32 v180, v169
	v_mov_b32_e32 v182, v171
	v_mov_b32_e32 v184, v173
	v_pk_add_f32 v[166:167], v[176:177], v[180:181]
	v_pk_add_f32 v[168:169], v[182:183], v[184:185]
	v_mul_f32_e32 v174, 0x3e800000, v175
	v_pk_add_f32 v[166:167], v[166:167], v[168:169]
	v_lshlrev_b64 v[168:169], 5, v[162:163]
	v_fmac_f32_e32 v166, 0x42800000, v167
	v_lshl_add_u64 v[168:169], s[6:7], 0, v[168:169]
	v_lshl_add_u64 v[168:169], s[2:3], 3, v[168:169]
	v_mov_b32_e32 v175, v166
	flat_store_dwordx2 v[168:169], v[174:175]
.LBB0_866:
	s_or_b64 exec, exec, s[0:1]
	s_waitcnt vmcnt(0)
	v_cmp_ne_u32_e64 s[44:45], 0, v164
	v_cmp_eq_u32_e64 s[42:43], 0, v164
	s_and_saveexec_b64 s[0:1], s[42:43]
	s_cbranch_execz .LBB0_869
	s_mov_b64 s[2:3], exec
	v_mbcnt_lo_u32_b32 v164, s2, 0
	v_mbcnt_hi_u32_b32 v164, s3, v164
	v_cmp_eq_u32_e32 vcc, 0, v164
	s_and_b64 s[4:5], exec, vcc
	s_mov_b64 exec, s[4:5]
	s_cbranch_execz .LBB0_869
	s_lshl_b32 s4, s68, 6
	s_ashr_i32 s5, s4, 31
	s_lshl_b64 s[4:5], s[4:5], 2
	v_readlane_b32 s8, v254, 7
	s_add_u32 s4, s8, s4
	v_readlane_b32 s8, v254, 8
	s_addc_u32 s5, s8, s5
	v_readlane_b32 s8, v254, 49
	v_readlane_b32 s2, v253, 2
	s_lshr_b32 s8, s8, 6
	s_lshl_b32 s8, s8, 3
	s_add_u32 s8, s8, s2
	s_lshl_b32 s8, s8, 2
	s_add_u32 s4, s4, s8
	s_addc_u32 s5, s5, 0
	v_mov_b32_e32 v164, 1
	global_store_dword v193, v164, s[4:5]
.LBB0_869:
	s_or_b64 exec, exec, s[0:1]
	v_readlane_b32 s0, v255, 7
	s_cmp_gt_u32 s0, 63
	s_cbranch_scc1 .LBB0_886
	v_mbcnt_lo_u32_b32 v186, -1, 0
	v_mbcnt_hi_u32_b32 v186, -1, v186
	v_and_b32_e32 v186, 31, v186
	v_lshlrev_b32_e32 v186, 2, v186
	s_memrealtime s[0:1]
	s_lshl_b32 s2, s68, 6
	s_ashr_i32 s3, s2, 31
	s_lshl_b64 s[2:3], s[2:3], 2
	v_readlane_b32 s4, v254, 7
	s_add_u32 s2, s4, s2
	v_readlane_b32 s4, v254, 8
	s_addc_u32 s3, s4, s3
	s_branch .LBB0_873

;     __device__ __forceinline__ bool run(const Acc& v, int pm, int pn, int wr, int wc, int fr, int fq, LAS unsigned char* lds, int wid, int lane) const {
;     ...
;             for (;;) {
;                 if ((unsigned)__builtin_amdgcn_readfirstlane(__hip_atomic_load(cnt + 64 * pm, __ATOMIC_RELAXED, __HIP_MEMORY_SCOPE_AGENT)) >= want) break;
;                 if (__builtin_amdgcn_s_memrealtime() - t0 > 2000000ull) {
;                     if (lane == 0) { unsigned expect = 0u; __hip_atomic_compare_exchange_strong(tmo + 1, &expect, code | (unsigned)(pm & 0xff), __ATOMIC_RELAXED, __ATOMIC_RELAXED, __HIP_MEMORY_SCOPE_AGENT);
;                                      __hip_atomic_store(tmo, 1u, __ATOMIC_RELAXED, __HIP_MEMORY_SCOPE_AGENT); }
;                     dead = true; break; }
;                 __builtin_amdgcn_s_sleep(2);
;             }
.LBB0_873:
	global_load_dword v164, v186, s[2:3] sc1
	s_mov_b64 s[8:9], -1
	s_mov_b64 s[10:11], -1
	s_waitcnt vmcnt(0)
	v_cmp_eq_u32_e32 vcc, 0, v164
	s_nop 1
	s_cmp_eq_u64 vcc, 0
	s_cbranch_scc1 .LBB0_872
	s_memrealtime s[4:5]
	v_mov_b64_e32 v[166:167], 0x1e8481
	s_waitcnt lgkmcnt(0)
	s_sub_u32 s4, s4, s0
	s_subb_u32 s5, s5, s1
	v_cmp_lt_u64_e32 vcc, s[4:5], v[166:167]
	s_cbranch_vccz .LBB0_871
	s_mov_b64 s[10:11], 0
	s_sleep 2
	s_branch .LBB0_871
